# mixer-branch / w_out decode-row tasks: both K trips' 16 loads in flight together (straight-line), MFMAs in original order
# baseline (speedup 1.0000x reference)
; #define LAS __attribute__((address_space(3)))
; DI void st8bf(bf16_t* p, f32x4 v0, f32x4 v1) { u32x4 w; w.x = pk2(v0.x, v0.y); w.y = pk2(v0.z, v0.w); w.z = pk2(v1.x, v1.y); w.w = pk2(v1.z, v1.w); *(u32x4*)p = w; }
;     DI void elem(int row, int col0, f32x4 v0, f32x4 v1) const { st8bf(H + (size_t)row * 512 + col0, v0, v1); }
;     DI void elem2(int row, int col0, f32x4 a0, f32x4 a1, f32x4 b0, f32x4 b1) const {
;         const bf16_t* p = GM + (size_t)row * 2048 + col0;
;         st8bf(MIX + (size_t)row * 1024 + col0, a0 * ld4bf(p) + b0 * ld4bf(p + 1024), a1 * ld4bf(p + 4) + b1 * ld4bf(p + 1028));
;     }
; template <class Epi>
; DI void skinny_task(LAS unsigned char* lds, const bf16_t* A, int lda, const bf16_t* Bt, int K, int n0, const Epi& E, int wave, int lane) {
;     ...
; #pragma unroll 2
;     for (int k = 0; k < ksl; k += 32) {
;         const bf16x8 a0 = *(const bf16x8*)(ap + k), a1 = *(const bf16x8*)(ap + (size_t)16 * lda + k);
;         const bf16x8 b0 = *(const bf16x8*)(bp + k), b1 = *(const bf16x8*)(bp + (size_t)4 * K + k);
;         acc[0][0] = __builtin_amdgcn_mfma_f32_16x16x32_bf16(b0, a0, acc[0][0], 0, 0, 0); acc[0][1] = __builtin_amdgcn_mfma_f32_16x16x32_bf16(b1, a0, acc[0][1], 0, 0, 0);
;         acc[1][0] = __builtin_amdgcn_mfma_f32_16x16x32_bf16(b0, a1, acc[1][0], 0, 0, 0); acc[1][1] = __builtin_amdgcn_mfma_f32_16x16x32_bf16(b1, a1, acc[1][1], 0, 0, 0);
;     }
;     LAS float* P = (LAS float*)lds;
;     __syncthreads();
; #pragma unroll
;     for (int mt = 0; mt < 2; ++mt)
; #pragma unroll
;         for (int nt = 0; nt < 2; ++nt) *(LAS f32x4*)(P + (wave * 32 + 16 * mt + fr) * 32 + 8 * fq + 4 * nt) = acc[mt][nt];
;     __syncthreads();
;     const int tid = wave * 64 + lane;
;     if (tid < 128) { const int row = tid >> 2, cg = tid & 3;
;         f32x4 s[2][2];
; #pragma unroll
;         for (int hf = 0; hf < 2; ++hf) { s[hf][0] = (f32x4){0.f, 0.f, 0.f, 0.f}; s[hf][1] = s[hf][0];
; #pragma unroll
;             for (int w = 0; w < 4; ++w) { const LAS float* p = P + ((4 * hf + w) * 32 + row) * 32 + 8 * cg; s[hf][0] = s[hf][0] + *(const LAS f32x4*)p; s[hf][1] = s[hf][1] + *(const LAS f32x4*)(p + 4); } }
;         if constexpr (Epi::HAS_MID) E.elem2(MPR + row, n0 + 8 * cg, s[0][0], s[0][1], s[1][0], s[1][1]);
;         else E.elem(MPR + row, n0 + 8 * cg, s[0][0] + s[1][0], s[0][1] + s[1][1]); }
.LBB0_2186:
	v_lshl_add_u64 v[36:37], v[32:33], 0, s[4:5]
	v_add_co_u32_e64 v60, s[0:1], s11, v36
	v_lshl_add_u64 v[38:39], v[30:31], 0, s[4:5]
	s_nop 0
	v_addc_co_u32_e64 v61, s[0:1], 0, v37, s[0:1]
	v_add_co_u32_e64 v64, s[0:1], s12, v36
	s_nop 0
	v_addc_co_u32_e64 v65, s[0:1], 0, v37, s[0:1]
	v_add_co_u32_e64 v62, s[0:1], s13, v38
	s_nop 0
	v_addc_co_u32_e64 v63, s[0:1], 0, v39, s[0:1]
	v_add_co_u32_e64 v66, s[0:1], s14, v38
	s_nop 0
	v_addc_co_u32_e64 v67, s[0:1], 0, v39, s[0:1]
	global_load_dwordx4 v[36:39], v[62:63], off
	global_load_dwordx4 v[40:43], v[60:61], off offset:2048
	global_load_dwordx4 v[44:47], v[66:67], off
	global_load_dwordx4 v[48:51], v[64:65], off offset:2048
	global_load_dwordx4 v[52:55], v[62:63], off offset:64
	global_load_dwordx4 v[56:59], v[60:61], off offset:2112
	global_load_dwordx4 v[116:119], v[66:67], off offset:64
	global_load_dwordx4 v[120:123], v[64:65], off offset:2112
	global_load_dwordx4 v[124:127], v[62:63], off offset:128
	global_load_dwordx4 v[128:131], v[60:61], off offset:2176
	global_load_dwordx4 v[132:135], v[66:67], off offset:128
	global_load_dwordx4 v[136:139], v[64:65], off offset:2176
	global_load_dwordx4 v[140:143], v[62:63], off offset:192
	global_load_dwordx4 v[144:147], v[60:61], off offset:2240
	global_load_dwordx4 v[148:151], v[66:67], off offset:192
	global_load_dwordx4 v[152:155], v[64:65], off offset:2240
	s_waitcnt vmcnt(14)
	v_mfma_f32_16x16x32_bf16 v[2:5], v[36:39], v[40:43], v[2:5]
	s_waitcnt vmcnt(13)
	v_mfma_f32_16x16x32_bf16 v[6:9], v[44:47], v[40:43], v[6:9]
	s_waitcnt vmcnt(12)
	v_mfma_f32_16x16x32_bf16 v[10:13], v[36:39], v[48:51], v[10:13]
	s_waitcnt vmcnt(12)
	v_mfma_f32_16x16x32_bf16 v[14:17], v[44:47], v[48:51], v[14:17]
	s_waitcnt vmcnt(10)
	v_mfma_f32_16x16x32_bf16 v[2:5], v[52:55], v[56:59], v[2:5]
	s_waitcnt vmcnt(9)
	v_mfma_f32_16x16x32_bf16 v[6:9], v[116:119], v[56:59], v[6:9]
	s_waitcnt vmcnt(8)
	v_mfma_f32_16x16x32_bf16 v[10:13], v[52:55], v[120:123], v[10:13]
	s_waitcnt vmcnt(8)
	v_mfma_f32_16x16x32_bf16 v[14:17], v[116:119], v[120:123], v[14:17]
	s_waitcnt vmcnt(6)
	v_mfma_f32_16x16x32_bf16 v[2:5], v[124:127], v[128:131], v[2:5]
	s_waitcnt vmcnt(5)
	v_mfma_f32_16x16x32_bf16 v[6:9], v[132:135], v[128:131], v[6:9]
	s_waitcnt vmcnt(4)
	v_mfma_f32_16x16x32_bf16 v[10:13], v[124:127], v[136:139], v[10:13]
	s_waitcnt vmcnt(4)
	v_mfma_f32_16x16x32_bf16 v[14:17], v[132:135], v[136:139], v[14:17]
	s_waitcnt vmcnt(2)
	v_mfma_f32_16x16x32_bf16 v[2:5], v[140:143], v[144:147], v[2:5]
	s_waitcnt vmcnt(1)
	v_mfma_f32_16x16x32_bf16 v[6:9], v[148:151], v[144:147], v[6:9]
	s_waitcnt vmcnt(0)
	v_mfma_f32_16x16x32_bf16 v[10:13], v[140:143], v[152:155], v[10:13]
	s_waitcnt vmcnt(0)
	v_mfma_f32_16x16x32_bf16 v[14:17], v[148:151], v[152:155], v[14:17]
	s_waitcnt lgkmcnt(0)
	s_barrier
	ds_write_b128 v22, v[2:5]
	s_nop 0
	ds_write_b128 v22, v[6:9] offset:16
	s_nop 0
	ds_write_b128 v22, v[10:13] offset:2048
	ds_write_b128 v22, v[14:17] offset:2064
	s_waitcnt lgkmcnt(0)
	s_barrier
	s_and_saveexec_b64 s[0:1], vcc
	s_cbranch_execz .LBB0_2184
	v_lshl_or_b32 v2, s8, 5, v34
	v_ashrrev_i32_e32 v3, 31, v2
	v_lshlrev_b64 v[88:89], 1, v[2:3]
	v_lshl_add_u64 v[10:11], v[18:19], 0, v[88:89]
	global_load_dwordx4 v[2:5], v[10:11], off
	global_load_dwordx4 v[6:9], v[10:11], off offset:2048
	ds_read_b128 v[10:13], v35
	ds_read_b128 v[14:17], v35 offset:16
	ds_read_b128 v[30:33], v35 offset:4096
	ds_read_b128 v[36:39], v35 offset:4112
	ds_read_b128 v[40:43], v35 offset:8192
	ds_read_b128 v[44:47], v35 offset:8208
	ds_read_b128 v[48:51], v35 offset:12288
	ds_read_b128 v[52:55], v35 offset:12304
	ds_read_b128 v[56:59], v35 offset:16384
	ds_read_b128 v[60:63], v35 offset:16400
	ds_read_b128 v[64:67], v35 offset:20480
	ds_read_b128 v[68:71], v35 offset:20496
	ds_read_b128 v[72:75], v35 offset:24576
	ds_read_b128 v[76:79], v35 offset:24592
	ds_read_b128 v[80:83], v35 offset:28672
	ds_read_b128 v[84:87], v35 offset:28688
	s_waitcnt lgkmcnt(14)
	v_pk_add_f32 v[12:13], v[12:13], 0 op_sel_hi:[1,0]
	v_pk_add_f32 v[10:11], v[10:11], 0 op_sel_hi:[1,0]
	v_pk_add_f32 v[16:17], v[16:17], 0 op_sel_hi:[1,0]
	v_pk_add_f32 v[14:15], v[14:15], 0 op_sel_hi:[1,0]
	s_waitcnt lgkmcnt(7)
	v_pk_add_f32 v[58:59], v[58:59], 0 op_sel_hi:[1,0]
	v_pk_add_f32 v[56:57], v[56:57], 0 op_sel_hi:[1,0]
	s_waitcnt lgkmcnt(6)
	v_pk_add_f32 v[62:63], v[62:63], 0 op_sel_hi:[1,0]
	v_pk_add_f32 v[60:61], v[60:61], 0 op_sel_hi:[1,0]
	v_pk_add_f32 v[12:13], v[12:13], v[32:33]
	v_pk_add_f32 v[10:11], v[10:11], v[30:31]
	v_pk_add_f32 v[16:17], v[16:17], v[38:39]
	v_pk_add_f32 v[14:15], v[14:15], v[36:37]
	s_waitcnt lgkmcnt(5)
	v_pk_add_f32 v[30:31], v[58:59], v[66:67]
	v_pk_add_f32 v[32:33], v[56:57], v[64:65]
	s_waitcnt lgkmcnt(4)
	v_pk_add_f32 v[36:37], v[62:63], v[70:71]
	v_pk_add_f32 v[38:39], v[60:61], v[68:69]
	s_waitcnt lgkmcnt(3)
	v_pk_add_f32 v[30:31], v[30:31], v[74:75]
	v_pk_add_f32 v[32:33], v[32:33], v[72:73]
	s_waitcnt lgkmcnt(2)
	v_pk_add_f32 v[36:37], v[36:37], v[78:79]
	v_pk_add_f32 v[38:39], v[38:39], v[76:77]
	v_pk_add_f32 v[12:13], v[12:13], v[42:43]
	v_pk_add_f32 v[10:11], v[10:11], v[40:41]
	v_pk_add_f32 v[16:17], v[16:17], v[46:47]
	v_pk_add_f32 v[14:15], v[14:15], v[44:45]
	s_waitcnt lgkmcnt(1)
	v_pk_add_f32 v[30:31], v[30:31], v[82:83]
	v_pk_add_f32 v[32:33], v[32:33], v[80:81]
	s_waitcnt lgkmcnt(0)
	v_pk_add_f32 v[36:37], v[36:37], v[86:87]
	v_pk_add_f32 v[38:39], v[38:39], v[84:85]
	v_pk_add_f32 v[12:13], v[12:13], v[50:51]
	v_pk_add_f32 v[10:11], v[10:11], v[48:49]
	v_pk_add_f32 v[16:17], v[16:17], v[54:55]
	v_pk_add_f32 v[14:15], v[14:15], v[52:53]
	v_lshl_add_u64 v[88:89], v[20:21], 0, v[88:89]
	s_waitcnt vmcnt(1)
	v_lshlrev_b32_e32 v40, 16, v2
	s_waitcnt vmcnt(0)
	v_lshlrev_b32_e32 v42, 16, v6
	v_and_b32_e32 v43, 0xffff0000, v6
	v_lshlrev_b32_e32 v6, 16, v7
	v_and_b32_e32 v7, 0xffff0000, v7
	v_lshlrev_b32_e32 v46, 16, v8
	v_and_b32_e32 v47, 0xffff0000, v8
	v_lshlrev_b32_e32 v8, 16, v9
	v_and_b32_e32 v9, 0xffff0000, v9
	v_and_b32_e32 v41, 0xffff0000, v2
	v_lshlrev_b32_e32 v2, 16, v3
	v_and_b32_e32 v3, 0xffff0000, v3
	v_lshlrev_b32_e32 v44, 16, v4
	v_and_b32_e32 v45, 0xffff0000, v4
	v_lshlrev_b32_e32 v4, 16, v5
	v_and_b32_e32 v5, 0xffff0000, v5
	v_pk_mul_f32 v[32:33], v[32:33], v[42:43]
	v_pk_mul_f32 v[6:7], v[30:31], v[6:7]
	v_pk_mul_f32 v[30:31], v[38:39], v[46:47]
	v_pk_mul_f32 v[8:9], v[36:37], v[8:9]
	v_pk_fma_f32 v[6:7], v[12:13], v[2:3], v[6:7]
	v_pk_fma_f32 v[2:3], v[10:11], v[40:41], v[32:33]
	v_pk_fma_f32 v[8:9], v[16:17], v[4:5], v[8:9]
	v_pk_fma_f32 v[4:5], v[14:15], v[44:45], v[30:31]
	v_cvt_pk_bf16_f32 v2, v2, v3
	v_cvt_pk_bf16_f32 v3, v6, v7
	v_cvt_pk_bf16_f32 v4, v4, v5
	v_cvt_pk_bf16_f32 v5, v8, v9
	global_store_dwordx4 v[88:89], v[2:5], off
	s_branch .LBB0_2184

;     DI void elem(int row, int col0, f32x4 v0, f32x4 v1) const {
;         if (row >= MREAL) return;
;         const int mrow = row < MPR ? (row >> 11) : 8 + (row - MPR);
;         const float* gp = mod + (size_t)mrow * 6144 + goff + col0;
;         f32x4 s0, s1;
;         if (xin) { s0 = ld4bf(xin + (size_t)row * D + col0); s1 = ld4bf(xin + (size_t)row * D + col0 + 4); }
;         else { const float* src = row < MPR ? xp + (size_t)row * D + col0 : xs + (size_t)(row - MPR) * D + col0; s0 = *(const f32x4*)src; s1 = *(const f32x4*)(src + 4); }
;         st8bf(XO + (size_t)row * D + col0, s0 + *(const f32x4*)gp * v0, s1 + *(const f32x4*)(gp + 4) * v1);
;     }
; template <class Epi>
; DI void skinny_task(LAS unsigned char* lds, const bf16_t* A, int lda, const bf16_t* Bt, int K, int n0, const Epi& E, int wave, int lane) {
;     ...
; #pragma unroll 2
;     for (int k = 0; k < ksl; k += 32) {
;         const bf16x8 a0 = *(const bf16x8*)(ap + k), a1 = *(const bf16x8*)(ap + (size_t)16 * lda + k);
;         const bf16x8 b0 = *(const bf16x8*)(bp + k), b1 = *(const bf16x8*)(bp + (size_t)4 * K + k);
;         acc[0][0] = __builtin_amdgcn_mfma_f32_16x16x32_bf16(b0, a0, acc[0][0], 0, 0, 0); acc[0][1] = __builtin_amdgcn_mfma_f32_16x16x32_bf16(b1, a0, acc[0][1], 0, 0, 0);
;         acc[1][0] = __builtin_amdgcn_mfma_f32_16x16x32_bf16(b0, a1, acc[1][0], 0, 0, 0); acc[1][1] = __builtin_amdgcn_mfma_f32_16x16x32_bf16(b1, a1, acc[1][1], 0, 0, 0);
;     }
;     LAS float* P = (LAS float*)lds;
;     __syncthreads();
; #pragma unroll
;     for (int mt = 0; mt < 2; ++mt)
; #pragma unroll
;         for (int nt = 0; nt < 2; ++nt) *(LAS f32x4*)(P + (wave * 32 + 16 * mt + fr) * 32 + 8 * fq + 4 * nt) = acc[mt][nt];
;     __syncthreads();
;     const int tid = wave * 64 + lane;
;     if (tid < 128) { const int row = tid >> 2, cg = tid & 3;
;         f32x4 s[2][2];
; #pragma unroll
;         for (int hf = 0; hf < 2; ++hf) { s[hf][0] = (f32x4){0.f, 0.f, 0.f, 0.f}; s[hf][1] = s[hf][0];
; #pragma unroll
;             for (int w = 0; w < 4; ++w) { const LAS float* p = P + ((4 * hf + w) * 32 + row) * 32 + 8 * cg; s[hf][0] = s[hf][0] + *(const LAS f32x4*)p; s[hf][1] = s[hf][1] + *(const LAS f32x4*)(p + 4); } }
;         if constexpr (Epi::HAS_MID) E.elem2(MPR + row, n0 + 8 * cg, s[0][0], s[0][1], s[1][0], s[1][1]);
;         else E.elem(MPR + row, n0 + 8 * cg, s[0][0] + s[1][0], s[0][1] + s[1][1]); }
.LBB0_2252:
	v_lshl_add_u64 v[38:39], v[34:35], 0, s[4:5]
	v_add_co_u32_e64 v62, s[0:1], s11, v38
	v_lshl_add_u64 v[40:41], v[32:33], 0, s[4:5]
	s_nop 0
	v_addc_co_u32_e64 v63, s[0:1], 0, v39, s[0:1]
	v_add_co_u32_e64 v66, s[0:1], s12, v38
	s_nop 0
	v_addc_co_u32_e64 v67, s[0:1], 0, v39, s[0:1]
	v_add_co_u32_e64 v64, s[0:1], s13, v40
	s_nop 0
	v_addc_co_u32_e64 v65, s[0:1], 0, v41, s[0:1]
	v_add_co_u32_e64 v68, s[0:1], s14, v40
	s_nop 0
	v_addc_co_u32_e64 v69, s[0:1], 0, v41, s[0:1]
	global_load_dwordx4 v[38:41], v[64:65], off
	global_load_dwordx4 v[42:45], v[62:63], off offset:2048
	global_load_dwordx4 v[46:49], v[68:69], off
	global_load_dwordx4 v[50:53], v[66:67], off offset:2048
	global_load_dwordx4 v[54:57], v[64:65], off offset:64
	global_load_dwordx4 v[58:61], v[62:63], off offset:2112
	global_load_dwordx4 v[116:119], v[68:69], off offset:64
	global_load_dwordx4 v[120:123], v[66:67], off offset:2112
	global_load_dwordx4 v[124:127], v[64:65], off offset:128
	global_load_dwordx4 v[128:131], v[62:63], off offset:2176
	global_load_dwordx4 v[132:135], v[68:69], off offset:128
	global_load_dwordx4 v[136:139], v[66:67], off offset:2176
	global_load_dwordx4 v[140:143], v[64:65], off offset:192
	global_load_dwordx4 v[144:147], v[62:63], off offset:2240
	global_load_dwordx4 v[148:151], v[68:69], off offset:192
	global_load_dwordx4 v[152:155], v[66:67], off offset:2240
	s_waitcnt vmcnt(14)
	v_mfma_f32_16x16x32_bf16 v[10:13], v[38:41], v[42:45], v[10:13]
	s_waitcnt vmcnt(13)
	v_mfma_f32_16x16x32_bf16 v[6:9], v[46:49], v[42:45], v[6:9]
	s_waitcnt vmcnt(12)
	v_mfma_f32_16x16x32_bf16 v[2:5], v[38:41], v[50:53], v[2:5]
	s_waitcnt vmcnt(12)
	v_mfma_f32_16x16x32_bf16 v[14:17], v[46:49], v[50:53], v[14:17]
	s_waitcnt vmcnt(10)
	v_mfma_f32_16x16x32_bf16 v[10:13], v[54:57], v[58:61], v[10:13]
	s_waitcnt vmcnt(9)
	v_mfma_f32_16x16x32_bf16 v[6:9], v[116:119], v[58:61], v[6:9]
	s_waitcnt vmcnt(8)
	v_mfma_f32_16x16x32_bf16 v[2:5], v[54:57], v[120:123], v[2:5]
	s_waitcnt vmcnt(8)
	v_mfma_f32_16x16x32_bf16 v[14:17], v[116:119], v[120:123], v[14:17]
	s_waitcnt vmcnt(6)
	v_mfma_f32_16x16x32_bf16 v[10:13], v[124:127], v[128:131], v[10:13]
	s_waitcnt vmcnt(5)
	v_mfma_f32_16x16x32_bf16 v[6:9], v[132:135], v[128:131], v[6:9]
	s_waitcnt vmcnt(4)
	v_mfma_f32_16x16x32_bf16 v[2:5], v[124:127], v[136:139], v[2:5]
	s_waitcnt vmcnt(4)
	v_mfma_f32_16x16x32_bf16 v[14:17], v[132:135], v[136:139], v[14:17]
	s_waitcnt vmcnt(2)
	v_mfma_f32_16x16x32_bf16 v[10:13], v[140:143], v[144:147], v[10:13]
	s_waitcnt vmcnt(1)
	v_mfma_f32_16x16x32_bf16 v[6:9], v[148:151], v[144:147], v[6:9]
	s_waitcnt vmcnt(0)
	v_mfma_f32_16x16x32_bf16 v[2:5], v[140:143], v[152:155], v[2:5]
	s_waitcnt vmcnt(0)
	v_mfma_f32_16x16x32_bf16 v[14:17], v[148:151], v[152:155], v[14:17]
	s_waitcnt lgkmcnt(0)
	s_barrier
	ds_write_b128 v18, v[10:13]
	s_nop 0
	ds_write_b128 v18, v[6:9] offset:16
	s_nop 0
	ds_write_b128 v18, v[2:5] offset:2048
	ds_write_b128 v18, v[14:17] offset:2064
	s_waitcnt lgkmcnt(0)
	s_barrier
	s_and_saveexec_b64 s[0:1], vcc
	s_cbranch_execz .LBB0_2250
	v_lshl_or_b32 v98, s8, 5, v36
	v_ashrrev_i32_e32 v99, 31, v98
	v_lshlrev_b64 v[2:3], 2, v[98:99]
	v_lshl_add_u64 v[32:33], v[20:21], 0, v[2:3]
	v_lshl_add_u64 v[34:35], v[22:23], 0, v[2:3]
	global_load_dwordx4 v[2:5], v[32:33], off
	global_load_dwordx4 v[6:9], v[34:35], off
	global_load_dwordx4 v[10:13], v[34:35], off offset:16
	global_load_dwordx4 v[14:17], v[32:33], off offset:16
	ds_read_b128 v[32:35], v37
	ds_read_b128 v[38:41], v37 offset:16
	ds_read_b128 v[42:45], v37 offset:4096
	ds_read_b128 v[46:49], v37 offset:4112
	ds_read_b128 v[50:53], v37 offset:8192
	ds_read_b128 v[54:57], v37 offset:8208
	ds_read_b128 v[58:61], v37 offset:12288
	ds_read_b128 v[62:65], v37 offset:12304
	ds_read_b128 v[66:69], v37 offset:16384
	ds_read_b128 v[70:73], v37 offset:16400
	ds_read_b128 v[74:77], v37 offset:20480
	ds_read_b128 v[78:81], v37 offset:20496
	ds_read_b128 v[82:85], v37 offset:24576
	ds_read_b128 v[86:89], v37 offset:24592
	ds_read_b128 v[90:93], v37 offset:28672
	ds_read_b128 v[94:97], v37 offset:28688
	s_waitcnt lgkmcnt(14)
	v_pk_add_f32 v[34:35], v[34:35], 0 op_sel_hi:[1,0]
	v_pk_add_f32 v[32:33], v[32:33], 0 op_sel_hi:[1,0]
	v_pk_add_f32 v[40:41], v[40:41], 0 op_sel_hi:[1,0]
	v_pk_add_f32 v[38:39], v[38:39], 0 op_sel_hi:[1,0]
	s_waitcnt lgkmcnt(7)
	v_pk_add_f32 v[68:69], v[68:69], 0 op_sel_hi:[1,0]
	v_pk_add_f32 v[66:67], v[66:67], 0 op_sel_hi:[1,0]
	s_waitcnt lgkmcnt(6)
	v_pk_add_f32 v[72:73], v[72:73], 0 op_sel_hi:[1,0]
	v_pk_add_f32 v[70:71], v[70:71], 0 op_sel_hi:[1,0]
	v_pk_add_f32 v[34:35], v[34:35], v[44:45]
	v_pk_add_f32 v[32:33], v[32:33], v[42:43]
	v_pk_add_f32 v[40:41], v[40:41], v[48:49]
	v_pk_add_f32 v[38:39], v[38:39], v[46:47]
	s_waitcnt lgkmcnt(5)
	v_pk_add_f32 v[42:43], v[68:69], v[76:77]
	v_pk_add_f32 v[44:45], v[66:67], v[74:75]
	s_waitcnt lgkmcnt(4)
	v_pk_add_f32 v[46:47], v[72:73], v[80:81]
	v_pk_add_f32 v[48:49], v[70:71], v[78:79]
	v_pk_add_f32 v[34:35], v[34:35], v[52:53]
	v_pk_add_f32 v[32:33], v[32:33], v[50:51]
	v_pk_add_f32 v[40:41], v[40:41], v[56:57]
	v_pk_add_f32 v[38:39], v[38:39], v[54:55]
	s_waitcnt lgkmcnt(3)
	v_pk_add_f32 v[42:43], v[42:43], v[84:85]
	v_pk_add_f32 v[44:45], v[44:45], v[82:83]
	s_waitcnt lgkmcnt(2)
	v_pk_add_f32 v[46:47], v[46:47], v[88:89]
	v_pk_add_f32 v[48:49], v[48:49], v[86:87]
	v_pk_add_f32 v[34:35], v[34:35], v[60:61]
	v_pk_add_f32 v[32:33], v[32:33], v[58:59]
	v_pk_add_f32 v[40:41], v[40:41], v[64:65]
	v_pk_add_f32 v[38:39], v[38:39], v[62:63]
	s_waitcnt lgkmcnt(1)
	v_pk_add_f32 v[42:43], v[42:43], v[92:93]
	v_pk_add_f32 v[44:45], v[44:45], v[90:91]
	s_waitcnt lgkmcnt(0)
	v_pk_add_f32 v[46:47], v[46:47], v[96:97]
	v_pk_add_f32 v[48:49], v[48:49], v[94:95]
	v_pk_add_f32 v[34:35], v[34:35], v[42:43]
	v_pk_add_f32 v[32:33], v[32:33], v[44:45]
	v_pk_add_f32 v[40:41], v[40:41], v[46:47]
	v_pk_add_f32 v[38:39], v[38:39], v[48:49]
	v_lshl_add_u64 v[98:99], v[98:99], 1, v[24:25]
	s_waitcnt vmcnt(2)
	v_pk_fma_f32 v[4:5], v[34:35], v[4:5], v[8:9]
	v_pk_fma_f32 v[2:3], v[32:33], v[2:3], v[6:7]
	s_waitcnt vmcnt(0)
	v_pk_fma_f32 v[6:7], v[40:41], v[16:17], v[12:13]
	v_pk_fma_f32 v[8:9], v[38:39], v[14:15], v[10:11]
	v_cvt_pk_bf16_f32 v2, v2, v3
	v_cvt_pk_bf16_f32 v3, v4, v5
	v_cvt_pk_bf16_f32 v4, v8, v9
	v_cvt_pk_bf16_f32 v5, v6, v7
	global_store_dwordx4 v[98:99], v[2:5], off
	s_branch .LBB0_2250
